# P1 norm_mod row loop: weight/scale/shift chunks 1-3 loaded up front with counted vmcnt (were 3 serialized round trips)
# speedup vs baseline: 1.0514x; 1.0022x over previous
; __device__ __forceinline__ unsigned pk2(float lo, float hi) { return pg8::cvt_pk_bf16(lo, hi); }
; __device__ __forceinline__ void norm_mod_phase(const float* xP, const float* xS, const float* g, const float* modl, int shift_i, int scale_i, bf16_t* outb, int lane, int wave, ...
;     ...
;     for (int sr = sgw; sr < TSAMPLE; sr += sngw) {
;         const int bb = 2 + (sr >> 6);
;         f32x4 v[4], pa[4];
; #pragma unroll
;         for (int j = 0; j < 4; ++j) { v[j] = *(const f32x4*)(xS + (size_t)sr * DM + 4 * (lane + 64 * j)); pa[j] = (f32x4){0.f, 0.f, 0.f, 0.f}; }
;         for (int sp0 = 0; sp0 < nsplit; sp0 += 4) {
;             f32x4 pv[4][4];
; #pragma unroll
;             for (int q = 0; q < 4; ++q) { const int sp = (sp0 + q < nsplit) ? sp0 + q : sp0;
; #pragma unroll
;                 for (int j = 0; j < 4; ++j) pv[q][j] = *(const f32x4*)(part + ((size_t)sp * TSAMPLE + sr) * DM + 4 * (lane + 64 * j)); }
; #pragma unroll
;             for (int q = 0; q < 4; ++q) if (sp0 + q < nsplit) {
; #pragma unroll
;                 for (int j = 0; j < 4; ++j) pa[j] = pa[j] + pv[q][j]; } }
;         if (nsplit > 0) {
; #pragma unroll
;             for (int j = 0; j < 4; ++j) { const int idx = 4 * (lane + 64 * j); v[j] = v[j] + (*(const f32x4*)(gatev + (size_t)bb * 6144 + idx) + 1.f) * pa[j];
;                 if (Xs) *(f32x4*)(Xs + (size_t)sr * DM + idx) = v[j]; } }
;         float ss = 0.f;
; #pragma unroll
;         for (int j = 0; j < 4; ++j) ss += (v[j].x * v[j].x + v[j].y * v[j].y) + (v[j].z * v[j].z + v[j].w * v[j].w);
;         const float rstd = rsqrtf(wave_sum(ss) * (1.f / DM) + EPSV);
;         if (outb) {
;             const float* sh = modl + (size_t)bb * 6144 + shift_i * 1024; const float* sc = modl + (size_t)bb * 6144 + scale_i * 1024;
; #pragma unroll
;             for (int j = 0; j < 4; ++j) { const int idx = 4 * (lane + 64 * j);
;                 const f32x4 y = v[j] * rstd * (*(const f32x4*)(g + idx)) * (*(const f32x4*)(sc + idx) + 1.f) + *(const f32x4*)(sh + idx);
;                 u32x2 w; w.x = pk2(y.x, y.y); w.y = pk2(y.z, y.w);
;                 *(u32x2*)(outb + (size_t)(TPROMPT + sr) * DM + idx) = w; }
.LBB0_145:
	global_load_dwordx4 v[22:25], v[8:9], off
	global_load_dwordx4 v[26:29], v[8:9], off offset:1024
	global_load_dwordx4 v[0:3], v[8:9], off offset:3072
	global_load_dwordx4 v[30:33], v[8:9], off offset:2048
	s_ashr_i32 s1, s8, 6
	s_add_i32 s1, s1, 2
	s_mul_hi_i32 s2, s1, 0x6000
	s_mulk_i32 s1, 0x6000
	s_add_u32 s14, s64, s1
	s_addc_u32 s15, s65, s2
	s_add_u32 s18, s14, 0x1000
	s_addc_u32 s19, s15, 0
	global_load_dwordx4 v[34:37], v[4:5], off
	global_load_dwordx4 v[38:41], v17, s[18:19]
	global_load_dwordx4 v[42:45], v17, s[14:15]
	global_load_dwordx4 v[170:173], v[4:5], off offset:1024
	global_load_dwordx4 v[174:177], v18, s[18:19]
	global_load_dwordx4 v[178:181], v17, s[14:15] offset:1024
	global_load_dwordx4 v[182:185], v[4:5], off offset:2048
	global_load_dwordx4 v[186:189], v19, s[18:19]
	global_load_dwordx4 v[190:193], v17, s[14:15] offset:2048
	global_load_dwordx4 v[194:197], v[4:5], off offset:3072
	global_load_dwordx4 v[198:201], v20, s[18:19]
	global_load_dwordx4 v[202:205], v17, s[14:15] offset:3072
	s_add_i32 s2, s8, 0x4000
	s_ashr_i32 s3, s2, 31
	s_lshl_b64 s[2:3], s[2:3], 11
	v_lshl_add_u64 v[46:47], v[6:7], 0, s[2:3]
	s_add_i32 s8, s8, s10
	v_lshl_add_u64 v[8:9], v[8:9], 0, s[12:13]
	s_cmpk_lt_i32 s8, 0x400
	s_waitcnt vmcnt(15)
	v_pk_mul_f32 v[48:49], v[24:25], v[24:25]
	v_pk_mul_f32 v[50:51], v[22:23], v[22:23]
	s_waitcnt vmcnt(14)
	v_pk_mul_f32 v[52:53], v[28:29], v[28:29]
	v_pk_mul_f32 v[54:55], v[26:27], v[26:27]
	v_pk_mov_b32 v[60:61], v[50:51], v[48:49] op_sel:[1,0]
	v_mov_b32_e32 v51, v49
	v_pk_mov_b32 v[48:49], v[54:55], v[52:53] op_sel:[1,0]
	v_mov_b32_e32 v55, v53
	s_waitcnt vmcnt(13)
	v_mul_f32_e32 v59, v1, v1
	s_waitcnt vmcnt(12)
	v_mul_f32_e32 v56, v31, v31
	v_mul_f32_e32 v58, v33, v33
	v_pk_add_f32 v[50:51], v[60:61], v[50:51]
	v_pk_add_f32 v[48:49], v[48:49], v[54:55]
	v_mul_f32_e32 v21, v0, v0
	v_mul_f32_e32 v62, v2, v2
	v_mul_f32_e32 v63, v3, v3
	v_pk_fma_f32 v[52:53], v[30:31], v[30:31], v[56:57] op_sel_hi:[1,1,0]
	v_pk_fma_f32 v[56:57], v[32:33], v[32:33], v[58:59] op_sel_hi:[1,1,0]
	v_pk_add_f32 v[50:51], v[50:51], v[50:51] op_sel:[0,1] op_sel_hi:[1,0]
	v_pk_add_f32 v[48:49], v[48:49], v[48:49] op_sel:[0,1] op_sel_hi:[1,0]
	v_mov_b32_e32 v53, v62
	v_mov_b32_e32 v57, v63
	v_mov_b32_e32 v51, v21
	v_mov_b32_e32 v49, v59
	v_pk_add_f32 v[52:53], v[52:53], v[56:57]
	v_pk_add_f32 v[48:49], v[50:51], v[48:49]
	s_waitcnt vmcnt(10)
	v_pk_add_f32 v[38:39], v[38:39], 1.0 op_sel_hi:[1,0]
	v_pk_add_f32 v[48:49], v[48:49], v[52:53]
	v_pk_add_f32 v[40:41], v[40:41], 1.0 op_sel_hi:[1,0]
	v_add_f32_e32 v21, v48, v49
	ds_bpermute_b32 v48, v10, v21
	s_waitcnt lgkmcnt(0)
	v_add_f32_e32 v21, v21, v48
	ds_bpermute_b32 v48, v11, v21
	s_waitcnt lgkmcnt(0)
	v_add_f32_e32 v21, v21, v48
	ds_bpermute_b32 v48, v12, v21
	s_waitcnt lgkmcnt(0)
	v_add_f32_e32 v21, v21, v48
	ds_bpermute_b32 v48, v13, v21
	s_waitcnt lgkmcnt(0)
	v_add_f32_e32 v21, v21, v48
	ds_bpermute_b32 v48, v14, v21
	s_waitcnt lgkmcnt(0)
	v_add_f32_e32 v21, v21, v48
	ds_bpermute_b32 v48, v15, v21
	s_waitcnt lgkmcnt(0)
	v_add_f32_e32 v21, v21, v48
	v_fmamk_f32 v21, v21, 0x3a800000, v16
	v_mul_f32_e32 v48, 0x4b800000, v21
	v_cmp_gt_f32_e32 vcc, s0, v21
	s_nop 1
	v_cndmask_b32_e32 v21, v21, v48, vcc
	v_rsq_f32_e32 v21, v21
	s_nop 0
	v_mul_f32_e32 v48, 0x45800000, v21
	v_cndmask_b32_e32 v48, v21, v48, vcc
	v_pk_mul_f32 v[22:23], v[22:23], v[48:49] op_sel_hi:[1,0]
	v_pk_mul_f32 v[24:25], v[24:25], v[48:49] op_sel_hi:[1,0]
	v_pk_mul_f32 v[22:23], v[34:35], v[22:23]
	v_pk_mul_f32 v[24:25], v[36:37], v[24:25]
	s_waitcnt vmcnt(9)
	v_pk_fma_f32 v[22:23], v[38:39], v[22:23], v[42:43]
	v_pk_fma_f32 v[24:25], v[40:41], v[24:25], v[44:45]
	v_cvt_pk_bf16_f32 v22, v22, v23
	v_pk_mul_f32 v[28:29], v[28:29], v[48:49] op_sel_hi:[1,0]
	v_cvt_pk_bf16_f32 v23, v24, v25
	global_store_dwordx2 v[46:47], v[22:23], off
	s_nop 0
	s_nop 0
	s_nop 0
	s_nop 0
	v_pk_mul_f32 v[26:27], v[26:27], v[48:49] op_sel_hi:[1,0]
	v_pk_mul_f32 v[30:31], v[30:31], v[48:49] op_sel_hi:[1,0]
	v_pk_mul_f32 v[32:33], v[32:33], v[48:49] op_sel_hi:[1,0]
	v_pk_mul_f32 v[2:3], v[2:3], v[48:49] op_sel_hi:[1,0]
	v_pk_mul_f32 v[0:1], v[0:1], v[48:49] op_sel_hi:[1,0]
	s_waitcnt vmcnt(9)
	v_pk_mul_f32 v[22:23], v[170:171], v[26:27]
	v_pk_mul_f32 v[24:25], v[172:173], v[28:29]
	s_waitcnt vmcnt(8)
	v_pk_add_f32 v[28:29], v[174:175], 1.0 op_sel_hi:[1,0]
	v_pk_add_f32 v[26:27], v[176:177], 1.0 op_sel_hi:[1,0]
	s_waitcnt vmcnt(7)
	v_pk_fma_f32 v[22:23], v[28:29], v[22:23], v[178:179]
	v_pk_fma_f32 v[24:25], v[26:27], v[24:25], v[180:181]
	v_cvt_pk_bf16_f32 v22, v22, v23
	s_nop 0
	v_cvt_pk_bf16_f32 v23, v24, v25
	global_store_dwordx2 v[46:47], v[22:23], off offset:512
	s_nop 0
	s_nop 0
	s_nop 0
	s_nop 0
	s_waitcnt vmcnt(7)
	v_pk_mul_f32 v[22:23], v[182:183], v[30:31]
	s_waitcnt vmcnt(6)
	v_pk_add_f32 v[26:27], v[186:187], 1.0 op_sel_hi:[1,0]
	v_pk_mul_f32 v[24:25], v[184:185], v[32:33]
	v_pk_add_f32 v[28:29], v[188:189], 1.0 op_sel_hi:[1,0]
	s_waitcnt vmcnt(5)
	v_pk_fma_f32 v[22:23], v[26:27], v[22:23], v[190:191]
	v_pk_fma_f32 v[24:25], v[28:29], v[24:25], v[192:193]
	v_cvt_pk_bf16_f32 v22, v22, v23
	s_nop 0
	v_cvt_pk_bf16_f32 v23, v24, v25
	global_store_dwordx2 v[46:47], v[22:23], off offset:1024
	s_nop 0
	s_nop 0
	s_nop 0
	s_nop 0
	s_waitcnt vmcnt(5)
	v_pk_mul_f32 v[0:1], v[0:1], v[194:195]
	v_pk_mul_f32 v[2:3], v[2:3], v[196:197]
	s_waitcnt vmcnt(4)
	v_pk_add_f32 v[24:25], v[198:199], 1.0 op_sel_hi:[1,0]
	v_pk_add_f32 v[22:23], v[200:201], 1.0 op_sel_hi:[1,0]
	s_waitcnt vmcnt(3)
	v_pk_fma_f32 v[0:1], v[0:1], v[24:25], v[202:203]
	v_pk_fma_f32 v[2:3], v[2:3], v[22:23], v[204:205]
	v_cvt_pk_bf16_f32 v0, v0, v1
	s_nop 0
	v_cvt_pk_bf16_f32 v1, v2, v3
	global_store_dwordx2 v[46:47], v[0:1], off offset:1536
	s_cbranch_scc1 .LBB0_145
